# SB item epilogue: output block staged through wave-private LDS and written with full-line dwordx4 stores
# baseline (speedup 1.0000x reference)
; template <int MODE>
; __device__ __forceinline__ void attn_item(const AttnP& p, int b, int h, int qb, LAS unsigned char* lds) {
;     ...
;     float inv0 = 1.f, inv1 = 0.f;
;     if (MODE != 1) { float l0 = lsum[0]; l0 += __shfl_xor(l0, 32); inv0 = 1.0f / l0; }
;     if (MODE == 0) { float l1 = lsum[NC - 1]; l1 += __shfl_xor(l1, 32); inv1 = p.lam / l1; }
;     float ss = 0.f;
; #pragma unroll
;     for (int d = 0; d < DV / 32; ++d)
; #pragma unroll
;         for (int i = 0; i < 16; ++i) {
;             float o = O[0][d][i] * inv0;
;             if (MODE == 0) o -= O[NC - 1][d][i] * inv1;
;             O[0][d][i] = o; ss += o * o;
;         }
;     ss += __shfl_xor(ss, 32);
;     float rn = 1.0f / sqrtf(ss * (1.0f / DV) + 1e-6f);
;     if (MODE == 0) rn *= p.oml;
;     int qrow_e = qrow; asm volatile("" : "+v"(qrow_e));
;     const size_t trow = (size_t)(tok0 + qrow_e);
; #pragma unroll
;     for (int d = 0; d < DV / 32; ++d)
; #pragma unroll
;         for (int g = 0; g < 4; ++g) {
;             const int dd = d * 32 + 8 * g + 4 * hh;
;             const u32x2 gr = *(const u32x2*)(P + trow * PP + gcol + dd);
;             const f32x4 og = *(const f32x4*)(p.out_gain + gaincol + dd);
.Lnx_bs:
	v_readfirstlane_b32 s100, v210
	s_lshr_b32 s100, s100, 6
	s_mul_i32 s100, s100, 0x1200
	s_add_i32 s100, s100, 0xb000
	v_and_b32_e32 v120, 31, v210
	v_bfe_u32 v121, v210, 5, 1
	v_mul_u32_u24_e32 v120, 0x90, v120
	v_lshl_add_u32 v120, v121, 3, v120
	v_add_u32_e32 v120, s100, v120
	v_mul_f32_e32 v0, v19, v19
	v_fmac_f32_e32 v0, v18, v18
	v_fmac_f32_e32 v0, v20, v20
	v_fmac_f32_e32 v0, v21, v21
	v_fmac_f32_e32 v0, v22, v22
	v_fmac_f32_e32 v0, v23, v23
	v_fmac_f32_e32 v0, v24, v24
	v_fmac_f32_e32 v0, v25, v25
	v_fmac_f32_e32 v0, v26, v26
	v_fmac_f32_e32 v0, v27, v27
	v_fmac_f32_e32 v0, v28, v28
	v_fmac_f32_e32 v0, v29, v29
	v_fmac_f32_e32 v0, v30, v30
	v_fmac_f32_e32 v0, v31, v31
	v_fmac_f32_e32 v0, v32, v32
	v_fmac_f32_e32 v0, v33, v33
	v_fmac_f32_e32 v0, v2, v2
	v_fmac_f32_e32 v0, v3, v3
	v_fmac_f32_e32 v0, v4, v4
	v_fmac_f32_e32 v0, v5, v5
	v_fmac_f32_e32 v0, v6, v6
	v_fmac_f32_e32 v0, v7, v7
	v_fmac_f32_e32 v0, v8, v8
	v_fmac_f32_e32 v0, v9, v9
	v_fmac_f32_e32 v0, v10, v10
	v_fmac_f32_e32 v0, v11, v11
	v_pk_mul_f32 v[38:39], v[12:13], v[12:13]
	v_pk_mul_f32 v[36:37], v[14:15], v[14:15]
	v_add_f32_e32 v0, v38, v0
	v_add_f32_e32 v0, v39, v0
	v_add_f32_e32 v0, v36, v0
	v_pk_mul_f32 v[34:35], v[16:17], v[16:17]
	v_add_f32_e32 v0, v37, v0
	v_add_f32_e32 v0, v34, v0
	v_add_f32_e32 v0, v35, v0
	ds_bpermute_b32 v34, v226, v0
	v_lshlrev_b32_e32 v39, 2, v87
	s_waitcnt lgkmcnt(0)
	v_add_f32_e32 v0, v0, v34
	v_fmamk_f32 v0, v0, 0x3c800000, v211
	v_cmp_gt_f32_e32 vcc, s74, v0
	v_mul_f32_e32 v34, 0x4f800000, v0
	s_nop 0
	v_cndmask_b32_e32 v0, v0, v34, vcc
	v_sqrt_f32_e32 v34, v0
	s_nop 0
	v_add_u32_e32 v35, -1, v34
	v_fma_f32 v36, -v35, v34, v0
	v_cmp_ge_f32_e64 s[0:1], 0, v36
	v_add_u32_e32 v36, 1, v34
	s_nop 0
	v_cndmask_b32_e64 v35, v34, v35, s[0:1]
	v_fma_f32 v34, -v36, v34, v0
	v_cmp_lt_f32_e64 s[0:1], 0, v34
	s_nop 1
	v_cndmask_b32_e64 v34, v35, v36, s[0:1]
	v_mul_f32_e32 v35, 0x37800000, v34
	v_cndmask_b32_e32 v34, v34, v35, vcc
	v_cmp_class_f32_e32 vcc, v0, v212
	s_nop 1
	v_cndmask_b32_e32 v0, v34, v0, vcc
	v_div_scale_f32 v34, s[0:1], v0, v0, 1.0
	v_rcp_f32_e32 v35, v34
	s_nop 0
	v_fma_f32 v36, -v34, v35, 1.0
	v_fmac_f32_e32 v35, v36, v35
	v_div_scale_f32 v36, vcc, 1.0, v0, 1.0
	v_mul_f32_e32 v37, v36, v35
	v_fma_f32 v38, -v34, v37, v36
	v_fmac_f32_e32 v37, v38, v35
	v_fma_f32 v34, -v34, v37, v36
	v_div_fmas_f32 v34, v34, v35, v37
	v_div_fixup_f32 v38, v34, v0, 1.0
	v_add_u32_e32 v34, s33, v86
	v_mov_b64_e32 v[36:37], s[46:47]
	v_mad_i64_i32 v[36:37], s[0:1], v34, s76, v[36:37]
	v_lshl_add_u64 v[36:37], v[36:37], 0, s[92:93]
	s_mov_b64 s[0:1], 0x1c00
	v_ashrrev_i32_e32 v35, 31, v34
	v_lshl_add_u64 v[40:41], v[36:37], 0, s[0:1]
	v_lshlrev_b32_e32 v0, 1, v87
	s_lshl_b32 s0, s20, 2
	v_lshlrev_b64 v[42:43], 11, v[34:35]
	v_lshl_add_u64 v[34:35], v[40:41], 0, v[0:1]
	s_add_u32 s0, s54, s0
	global_load_dwordx2 v[44:45], v[34:35], off
	global_load_dwordx2 v[122:123], v[34:35], off offset:16
	global_load_dwordx2 v[124:125], v[34:35], off offset:32
	global_load_dwordx2 v[126:127], v[34:35], off offset:48
	global_load_dwordx2 v[128:129], v[34:35], off offset:64
	global_load_dwordx2 v[130:131], v[34:35], off offset:80
	global_load_dwordx2 v[132:133], v[34:35], off offset:96
	global_load_dwordx2 v[134:135], v[34:35], off offset:112
	s_addc_u32 s1, s55, 0
	global_load_dwordx4 v[34:37], v39, s[0:1] offset:2048
	global_load_dwordx4 v[136:139], v39, s[0:1] offset:2080
	global_load_dwordx4 v[140:143], v39, s[0:1] offset:2112
	global_load_dwordx4 v[144:147], v39, s[0:1] offset:2144
	global_load_dwordx4 v[148:151], v39, s[0:1] offset:2176
	global_load_dwordx4 v[152:155], v39, s[0:1] offset:2208
	global_load_dwordx4 v[156:159], v39, s[0:1] offset:2240
	global_load_dwordx4 v[160:163], v39, s[0:1] offset:2272
	v_pk_mul_f32 v[18:19], v[18:19], v[38:39] op_sel_hi:[1,0]
	v_pk_mul_f32 v[20:21], v[20:21], v[38:39] op_sel_hi:[1,0]
	v_pk_mul_f32 v[22:23], v[22:23], v[38:39] op_sel_hi:[1,0]
	v_pk_mul_f32 v[24:25], v[24:25], v[38:39] op_sel_hi:[1,0]
	v_pk_mul_f32 v[26:27], v[26:27], v[38:39] op_sel_hi:[1,0]
	v_pk_mul_f32 v[28:29], v[28:29], v[38:39] op_sel_hi:[1,0]
	v_pk_mul_f32 v[30:31], v[30:31], v[38:39] op_sel_hi:[1,0]
	v_pk_mul_f32 v[2:3], v[2:3], v[38:39] op_sel_hi:[1,0]
	v_pk_mul_f32 v[4:5], v[4:5], v[38:39] op_sel_hi:[1,0]
	v_pk_mul_f32 v[6:7], v[6:7], v[38:39] op_sel_hi:[1,0]
	v_pk_mul_f32 v[8:9], v[8:9], v[38:39] op_sel_hi:[1,0]
	v_pk_mul_f32 v[10:11], v[10:11], v[38:39] op_sel_hi:[1,0]
	s_waitcnt vmcnt(0) lgkmcnt(0)
; __device__ __forceinline__ unsigned pk2(float lo, float hi) { f32x2 v = {lo, hi}; bf16x2_t b = __builtin_convertvector(v, bf16x2_t); return __builtin_bit_cast(unsigned, b); }
; __device__ __forceinline__ float bflo(unsigned u) { return __uint_as_float(u << 16); }
; __device__ __forceinline__ float bfhi(unsigned u) { return __uint_as_float(u & 0xffff0000u); }
; __device__ __forceinline__ float silu(float g) { return g * __builtin_amdgcn_rcpf(1.0f + __expf(-g)); }
; template <int MODE>
; __device__ __forceinline__ void attn_item(const AttnP& p, int b, int h, int qb, LAS unsigned char* lds) {
;     ...
; #pragma unroll
;     for (int d = 0; d < DV / 32; ++d)
; #pragma unroll
;         for (int g = 0; g < 4; ++g) {
;             const int dd = d * 32 + 8 * g + 4 * hh;
;             const u32x2 gr = *(const u32x2*)(P + trow * PP + gcol + dd);
;             const f32x4 og = *(const f32x4*)(p.out_gain + gaincol + dd);
;             const float o0 = O[0][d][4 * g] * rn * og[0] * silu(bflo(gr.x)), o1 = O[0][d][4 * g + 1] * rn * og[1] * silu(bfhi(gr.x));
;             const float o2 = O[0][d][4 * g + 2] * rn * og[2] * silu(bflo(gr.y)), o3 = O[0][d][4 * g + 3] * rn * og[3] * silu(bfhi(gr.y));
;             u32x2 wv; wv.x = pk2(o0, o1); wv.y = pk2(o2, o3);
;             *(u32x2*)(p.mixed + trow * 1024 + mixcol + dd) = wv;
	v_lshlrev_b32_e32 v46, 16, v44
	v_and_b32_e32 v47, 0xffff0000, v44
	v_mul_f32_e32 v44, 0xbfb8aa3b, v46
	v_pk_mul_f32 v[18:19], v[34:35], v[18:19]
	v_mul_f32_e32 v34, 0xbfb8aa3b, v47
	v_exp_f32_e32 v44, v44
	v_exp_f32_e32 v34, v34
	v_pk_mul_f32 v[20:21], v[36:37], v[20:21]
	v_add_f32_e32 v44, 1.0, v44
	v_add_f32_e32 v34, 1.0, v34
	v_rcp_f32_e32 v48, v44
	v_rcp_f32_e32 v49, v34
	s_nop 0
	v_pk_mul_f32 v[34:35], v[48:49], v[46:47]
	s_nop 0
	v_pk_mul_f32 v[18:19], v[18:19], v[34:35]
	v_lshlrev_b32_e32 v34, 16, v45
	v_and_b32_e32 v35, 0xffff0000, v45
	v_mul_f32_e32 v44, 0xbfb8aa3b, v34
	v_mul_f32_e32 v36, 0xbfb8aa3b, v35
	v_exp_f32_e32 v44, v44
	v_exp_f32_e32 v36, v36
	v_add_f32_e32 v44, 1.0, v44
	v_add_f32_e32 v36, 1.0, v36
	v_rcp_f32_e32 v44, v44
	v_rcp_f32_e32 v45, v36
	s_nop 0
	v_pk_mul_f32 v[34:35], v[44:45], v[34:35]
	s_nop 0
	v_pk_mul_f32 v[20:21], v[20:21], v[34:35]
	v_cvt_pk_bf16_f32 v34, v18, v19
	v_lshl_add_u64 v[18:19], s[44:45], 0, v[42:43]
	v_lshl_add_u64 v[18:19], v[18:19], 0, s[92:93]
	v_cvt_pk_bf16_f32 v35, v20, v21
	v_lshl_add_u64 v[18:19], v[18:19], 0, v[0:1]
	v_or_b32_e32 v20, 16, v0
	v_mov_b32_e32 v21, v1
	ds_write_b64 v120, v[34:35] offset:0
	v_lshl_add_u64 v[20:21], v[40:41], 0, v[20:21]
	v_mov_b64_e32 v[20:21], v[122:123]
	s_nop 0
	v_mov_b64_e32 v[34:35], v[136:137]
	v_mov_b64_e32 v[36:37], v[138:139]
	v_lshlrev_b32_e32 v42, 16, v20
	v_and_b32_e32 v43, 0xffff0000, v20
	v_mul_f32_e32 v20, 0xbfb8aa3b, v42
	v_exp_f32_e32 v20, v20
	v_pk_mul_f32 v[22:23], v[34:35], v[22:23]
	v_pk_mul_f32 v[24:25], v[36:37], v[24:25]
	v_add_f32_e32 v20, 1.0, v20
	v_rcp_f32_e32 v44, v20
	v_mul_f32_e32 v20, 0xbfb8aa3b, v43
	v_exp_f32_e32 v20, v20
	s_nop 0
	v_add_f32_e32 v20, 1.0, v20
	v_rcp_f32_e32 v45, v20
	v_lshlrev_b32_e32 v20, 16, v21
	v_and_b32_e32 v21, 0xffff0000, v21
	v_pk_mul_f32 v[34:35], v[44:45], v[42:43]
	s_nop 0
	v_pk_mul_f32 v[22:23], v[22:23], v[34:35]
	v_mul_f32_e32 v34, 0xbfb8aa3b, v20
	v_mul_f32_e32 v35, 0xbfb8aa3b, v21
	v_exp_f32_e32 v34, v34
	v_exp_f32_e32 v35, v35
	v_cvt_pk_bf16_f32 v22, v22, v23
	v_add_f32_e32 v34, 1.0, v34
	v_add_f32_e32 v35, 1.0, v35
	v_rcp_f32_e32 v34, v34
	v_rcp_f32_e32 v35, v35
	s_nop 0
	v_pk_mul_f32 v[20:21], v[34:35], v[20:21]
	s_nop 0
	v_pk_mul_f32 v[20:21], v[24:25], v[20:21]
	s_nop 0
	v_cvt_pk_bf16_f32 v23, v20, v21
	v_or_b32_e32 v20, 32, v0
	v_mov_b32_e32 v21, v1
	ds_write_b64 v120, v[22:23] offset:16
	v_lshl_add_u64 v[20:21], v[40:41], 0, v[20:21]
	v_mov_b64_e32 v[24:25], v[124:125]
	s_nop 0
	v_mov_b64_e32 v[20:21], v[140:141]
	v_mov_b64_e32 v[22:23], v[142:143]
	v_lshlrev_b32_e32 v34, 16, v24
	v_and_b32_e32 v35, 0xffff0000, v24
	v_mul_f32_e32 v24, 0xbfb8aa3b, v34
	v_exp_f32_e32 v24, v24
	v_pk_mul_f32 v[20:21], v[26:27], v[20:21]
	v_pk_mul_f32 v[22:23], v[28:29], v[22:23]
	v_add_f32_e32 v24, 1.0, v24
	v_rcp_f32_e32 v36, v24
	v_mul_f32_e32 v24, 0xbfb8aa3b, v35
	v_exp_f32_e32 v24, v24
	s_nop 0
	v_add_f32_e32 v24, 1.0, v24
	v_rcp_f32_e32 v37, v24
	v_lshlrev_b32_e32 v24, 16, v25
	v_and_b32_e32 v25, 0xffff0000, v25
	v_pk_mul_f32 v[26:27], v[36:37], v[34:35]
	s_nop 0
	v_pk_mul_f32 v[20:21], v[20:21], v[26:27]
	v_mul_f32_e32 v26, 0xbfb8aa3b, v24
	v_mul_f32_e32 v27, 0xbfb8aa3b, v25
	v_exp_f32_e32 v26, v26
	v_exp_f32_e32 v27, v27
	v_cvt_pk_bf16_f32 v20, v20, v21
	v_add_f32_e32 v26, 1.0, v26
	v_add_f32_e32 v27, 1.0, v27
	v_rcp_f32_e32 v26, v26
	v_rcp_f32_e32 v27, v27
	s_nop 0
	v_pk_mul_f32 v[24:25], v[26:27], v[24:25]
	s_nop 0
	v_pk_mul_f32 v[22:23], v[22:23], v[24:25]
	s_nop 0
	v_cvt_pk_bf16_f32 v21, v22, v23
	ds_write_b64 v120, v[20:21] offset:32
	v_or_b32_e32 v20, 48, v0
	v_mov_b32_e32 v21, v1
	v_lshl_add_u64 v[20:21], v[40:41], 0, v[20:21]
	v_mov_b64_e32 v[24:25], v[126:127]
	s_nop 0
	v_mov_b64_e32 v[20:21], v[144:145]
	v_mov_b64_e32 v[22:23], v[146:147]
	v_lshlrev_b32_e32 v26, 16, v24
	v_and_b32_e32 v27, 0xffff0000, v24
	v_mul_f32_e32 v24, 0xbfb8aa3b, v26
	v_exp_f32_e32 v24, v24
	v_pk_mul_f32 v[20:21], v[30:31], v[20:21]
	v_add_f32_e32 v24, 1.0, v24
	v_rcp_f32_e32 v28, v24
	v_mul_f32_e32 v24, 0xbfb8aa3b, v27
	v_exp_f32_e32 v24, v24
	s_nop 0
	v_add_f32_e32 v24, 1.0, v24
	v_rcp_f32_e32 v29, v24
	v_lshlrev_b32_e32 v24, 16, v25
	v_and_b32_e32 v25, 0xffff0000, v25
	v_pk_mul_f32 v[26:27], v[28:29], v[26:27]
	s_nop 0
	v_pk_mul_f32 v[20:21], v[20:21], v[26:27]
	v_mul_f32_e32 v26, 0xbfb8aa3b, v24
	v_mul_f32_e32 v27, 0xbfb8aa3b, v25
	v_exp_f32_e32 v26, v26
	v_exp_f32_e32 v27, v27
	v_pk_mul_f32 v[28:29], v[32:33], v[38:39] op_sel_hi:[1,0]
	v_cvt_pk_bf16_f32 v20, v20, v21
	v_add_f32_e32 v26, 1.0, v26
	v_add_f32_e32 v27, 1.0, v27
	v_rcp_f32_e32 v26, v26
	v_rcp_f32_e32 v27, v27
	v_pk_mul_f32 v[22:23], v[28:29], v[22:23]
	v_pk_mul_f32 v[24:25], v[26:27], v[24:25]
	s_nop 0
	v_pk_mul_f32 v[22:23], v[22:23], v[24:25]
	s_nop 0
	v_cvt_pk_bf16_f32 v21, v22, v23
	ds_write_b64 v120, v[20:21] offset:48
	v_or_b32_e32 v20, 64, v0
	v_mov_b32_e32 v21, v1
	v_lshl_add_u64 v[20:21], v[40:41], 0, v[20:21]
	v_mov_b64_e32 v[20:21], v[128:129]
	s_nop 0
	v_mov_b64_e32 v[22:23], v[148:149]
	v_mov_b64_e32 v[24:25], v[150:151]
	v_lshlrev_b32_e32 v26, 16, v20
	v_and_b32_e32 v27, 0xffff0000, v20
	v_mul_f32_e32 v20, 0xbfb8aa3b, v26
	v_exp_f32_e32 v20, v20
	v_pk_mul_f32 v[2:3], v[2:3], v[22:23]
	v_pk_mul_f32 v[4:5], v[4:5], v[24:25]
	v_add_f32_e32 v20, 1.0, v20
	v_rcp_f32_e32 v28, v20
	v_mul_f32_e32 v20, 0xbfb8aa3b, v27
	v_exp_f32_e32 v20, v20
	s_nop 0
	v_add_f32_e32 v20, 1.0, v20
	v_rcp_f32_e32 v29, v20
	v_lshlrev_b32_e32 v20, 16, v21
	v_and_b32_e32 v21, 0xffff0000, v21
; __device__ __forceinline__ unsigned pk2(float lo, float hi) { f32x2 v = {lo, hi}; bf16x2_t b = __builtin_convertvector(v, bf16x2_t); return __builtin_bit_cast(unsigned, b); }
; __device__ __forceinline__ float bflo(unsigned u) { return __uint_as_float(u << 16); }
; __device__ __forceinline__ float bfhi(unsigned u) { return __uint_as_float(u & 0xffff0000u); }
; __device__ __forceinline__ float silu(float g) { return g * __builtin_amdgcn_rcpf(1.0f + __expf(-g)); }
; template <int MODE>
; __device__ __forceinline__ void attn_item(const AttnP& p, int b, int h, int qb, LAS unsigned char* lds) {
;     ...
; #pragma unroll
;     for (int d = 0; d < DV / 32; ++d)
; #pragma unroll
;         for (int g = 0; g < 4; ++g) {
;             const int dd = d * 32 + 8 * g + 4 * hh;
;             const u32x2 gr = *(const u32x2*)(P + trow * PP + gcol + dd);
;             const f32x4 og = *(const f32x4*)(p.out_gain + gaincol + dd);
;             const float o0 = O[0][d][4 * g] * rn * og[0] * silu(bflo(gr.x)), o1 = O[0][d][4 * g + 1] * rn * og[1] * silu(bfhi(gr.x));
;             const float o2 = O[0][d][4 * g + 2] * rn * og[2] * silu(bflo(gr.y)), o3 = O[0][d][4 * g + 3] * rn * og[3] * silu(bfhi(gr.y));
;             u32x2 wv; wv.x = pk2(o0, o1); wv.y = pk2(o2, o3);
;             *(u32x2*)(p.mixed + trow * 1024 + mixcol + dd) = wv;
	v_pk_mul_f32 v[22:23], v[28:29], v[26:27]
	s_nop 0
	v_pk_mul_f32 v[2:3], v[2:3], v[22:23]
	v_mul_f32_e32 v22, 0xbfb8aa3b, v20
	v_mul_f32_e32 v23, 0xbfb8aa3b, v21
	v_exp_f32_e32 v22, v22
	v_exp_f32_e32 v23, v23
	v_cvt_pk_bf16_f32 v2, v2, v3
	v_add_f32_e32 v22, 1.0, v22
	v_add_f32_e32 v23, 1.0, v23
	v_rcp_f32_e32 v22, v22
	v_rcp_f32_e32 v23, v23
	s_nop 0
	v_pk_mul_f32 v[20:21], v[22:23], v[20:21]
	s_nop 0
	v_pk_mul_f32 v[4:5], v[4:5], v[20:21]
	s_nop 0
	v_cvt_pk_bf16_f32 v3, v4, v5
	ds_write_b64 v120, v[2:3] offset:64
	v_or_b32_e32 v2, 0x50, v0
	v_mov_b32_e32 v3, v1
	v_lshl_add_u64 v[2:3], v[40:41], 0, v[2:3]
	v_mov_b64_e32 v[20:21], v[130:131]
	s_nop 0
	v_mov_b64_e32 v[2:3], v[152:153]
	v_mov_b64_e32 v[4:5], v[154:155]
	v_lshlrev_b32_e32 v22, 16, v20
	v_and_b32_e32 v23, 0xffff0000, v20
	v_mul_f32_e32 v20, 0xbfb8aa3b, v22
	v_pk_mul_f32 v[2:3], v[6:7], v[2:3]
	v_mul_f32_e32 v6, 0xbfb8aa3b, v23
	v_exp_f32_e32 v20, v20
	v_exp_f32_e32 v6, v6
	v_pk_mul_f32 v[4:5], v[8:9], v[4:5]
	v_add_f32_e32 v20, 1.0, v20
	v_add_f32_e32 v6, 1.0, v6
	v_rcp_f32_e32 v24, v20
	v_rcp_f32_e32 v25, v6
	s_nop 0
	v_pk_mul_f32 v[6:7], v[24:25], v[22:23]
	s_nop 0
	v_pk_mul_f32 v[2:3], v[2:3], v[6:7]
	v_lshlrev_b32_e32 v6, 16, v21
	v_and_b32_e32 v7, 0xffff0000, v21
	v_mul_f32_e32 v20, 0xbfb8aa3b, v6
	v_mul_f32_e32 v8, 0xbfb8aa3b, v7
	v_exp_f32_e32 v20, v20
	v_exp_f32_e32 v8, v8
	v_cvt_pk_bf16_f32 v2, v2, v3
	v_add_f32_e32 v20, 1.0, v20
	v_add_f32_e32 v8, 1.0, v8
	v_rcp_f32_e32 v20, v20
	v_rcp_f32_e32 v21, v8
	s_nop 0
	v_pk_mul_f32 v[6:7], v[20:21], v[6:7]
	s_nop 0
	v_pk_mul_f32 v[4:5], v[4:5], v[6:7]
	s_nop 0
	v_cvt_pk_bf16_f32 v3, v4, v5
	ds_write_b64 v120, v[2:3] offset:80
	v_or_b32_e32 v2, 0x60, v0
	v_mov_b32_e32 v3, v1
	v_lshl_add_u64 v[2:3], v[40:41], 0, v[2:3]
	v_mov_b64_e32 v[6:7], v[132:133]
	s_nop 0
	v_mov_b64_e32 v[2:3], v[156:157]
	v_mov_b64_e32 v[4:5], v[158:159]
	v_or_b32_e32 v0, 0x70, v0
	v_lshlrev_b32_e32 v8, 16, v6
	v_and_b32_e32 v9, 0xffff0000, v6
	v_mul_f32_e32 v6, 0xbfb8aa3b, v8
	v_exp_f32_e32 v6, v6
	v_pk_mul_f32 v[2:3], v[10:11], v[2:3]
	v_pk_mul_f32 v[10:11], v[12:13], v[38:39] op_sel_hi:[1,0]
	v_pk_mul_f32 v[12:13], v[14:15], v[38:39] op_sel_hi:[1,0]
	v_add_f32_e32 v6, 1.0, v6
	v_rcp_f32_e32 v20, v6
	v_mul_f32_e32 v6, 0xbfb8aa3b, v9
	v_exp_f32_e32 v6, v6
	v_pk_mul_f32 v[4:5], v[10:11], v[4:5]
	v_add_f32_e32 v6, 1.0, v6
	v_rcp_f32_e32 v21, v6
	v_lshlrev_b32_e32 v6, 16, v7
	v_and_b32_e32 v7, 0xffff0000, v7
	v_pk_mul_f32 v[8:9], v[20:21], v[8:9]
	s_nop 0
	v_pk_mul_f32 v[2:3], v[2:3], v[8:9]
	v_mul_f32_e32 v8, 0xbfb8aa3b, v6
	v_mul_f32_e32 v9, 0xbfb8aa3b, v7
	v_exp_f32_e32 v8, v8
	v_exp_f32_e32 v9, v9
	v_cvt_pk_bf16_f32 v2, v2, v3
	v_add_f32_e32 v8, 1.0, v8
	v_add_f32_e32 v9, 1.0, v9
	v_rcp_f32_e32 v8, v8
	v_rcp_f32_e32 v9, v9
	s_nop 0
	v_pk_mul_f32 v[6:7], v[8:9], v[6:7]
	s_nop 0
	v_pk_mul_f32 v[4:5], v[4:5], v[6:7]
	s_nop 0
	v_cvt_pk_bf16_f32 v3, v4, v5
	ds_write_b64 v120, v[2:3] offset:96
	v_lshl_add_u64 v[2:3], v[40:41], 0, v[0:1]
	v_mov_b64_e32 v[2:3], v[134:135]
	s_nop 0
	v_mov_b64_e32 v[4:5], v[160:161]
	v_mov_b64_e32 v[6:7], v[162:163]
	s_mov_b64 s[0:1], 0
	v_lshlrev_b32_e32 v8, 16, v2
	v_mul_f32_e32 v0, 0xbfb8aa3b, v8
	v_exp_f32_e32 v0, v0
	v_and_b32_e32 v9, 0xffff0000, v2
	v_lshlrev_b32_e32 v2, 16, v3
	v_pk_mul_f32 v[4:5], v[12:13], v[4:5]
	v_add_f32_e32 v0, 1.0, v0
	v_rcp_f32_e32 v10, v0
	v_mul_f32_e32 v0, 0xbfb8aa3b, v9
	v_exp_f32_e32 v0, v0
	v_and_b32_e32 v3, 0xffff0000, v3
	v_add_f32_e32 v0, 1.0, v0
	v_rcp_f32_e32 v11, v0
	v_mul_f32_e32 v0, 0xbfb8aa3b, v2
	v_exp_f32_e32 v0, v0
	v_pk_mul_f32 v[8:9], v[10:11], v[8:9]
	s_nop 0
	v_pk_mul_f32 v[4:5], v[4:5], v[8:9]
	v_add_f32_e32 v0, 1.0, v0
	v_rcp_f32_e32 v8, v0
	v_mul_f32_e32 v0, 0xbfb8aa3b, v3
	v_exp_f32_e32 v0, v0
	v_pk_mul_f32 v[10:11], v[16:17], v[38:39] op_sel_hi:[1,0]
	v_cvt_pk_bf16_f32 v4, v4, v5
	v_pk_mul_f32 v[6:7], v[10:11], v[6:7]
	v_add_f32_e32 v0, 1.0, v0
	v_rcp_f32_e32 v9, v0
	s_nop 0
	v_pk_mul_f32 v[2:3], v[8:9], v[2:3]
	s_nop 0
	v_pk_mul_f32 v[2:3], v[6:7], v[2:3]
	s_nop 0
	v_cvt_pk_bf16_f32 v5, v2, v3
	ds_write_b64 v120, v[4:5] offset:112
	v_and_b32_e32 v121, 63, v210
	v_lshrrev_b32_e32 v122, 3, v121
	v_and_b32_e32 v121, 7, v121
	v_mul_u32_u24_e32 v123, 0x90, v122
	v_lshl_add_u32 v123, v121, 4, v123
	v_add_u32_e32 v123, s100, v123
	s_waitcnt lgkmcnt(0)
	ds_read_b128 v[128:131], v123
	ds_read_b128 v[132:135], v123 offset:1152
	ds_read_b128 v[136:139], v123 offset:2304
	ds_read_b128 v[140:143], v123 offset:3456
	v_readfirstlane_b32 s101, v86
	s_add_i32 s101, s101, s33
	v_add_u32_e32 v124, s101, v122
	v_mov_b32_e32 v125, 0
	v_lshlrev_b64 v[124:125], 11, v[124:125]
	v_lshl_add_u64 v[124:125], s[44:45], 0, v[124:125]
	v_lshl_add_u64 v[124:125], v[124:125], 0, s[92:93]
	v_lshlrev_b32_e32 v126, 4, v121
	v_mov_b32_e32 v127, 0
	v_lshl_add_u64 v[124:125], v[124:125], 0, v[126:127]
	s_waitcnt lgkmcnt(3)
	global_store_dwordx4 v[124:125], v[128:131], off offset:1024
	v_add_co_u32_e32 v124, vcc, 0x4000, v124
	s_nop 1
	v_addc_co_u32_e32 v125, vcc, 0, v125, vcc
	s_waitcnt lgkmcnt(2)
	global_store_dwordx4 v[124:125], v[132:135], off offset:1024
	v_add_co_u32_e32 v124, vcc, 0x4000, v124
	s_nop 1
	v_addc_co_u32_e32 v125, vcc, 0, v125, vcc
	s_waitcnt lgkmcnt(1)
	global_store_dwordx4 v[124:125], v[136:139], off offset:1024
	v_add_co_u32_e32 v124, vcc, 0x4000, v124
	s_nop 1
	v_addc_co_u32_e32 v125, vcc, 0, v125, vcc
	s_waitcnt lgkmcnt(0)
	global_store_dwordx4 v[124:125], v[140:143], off offset:1024
